# SwiGLU epilogues (FFN up GEMMs) re-emitted: packed f32 mul/add, 16 elements software-pipelined per step, no hazard nops; same f32 math order
# speedup vs baseline: 1.0074x; 1.0074x over previous
; __device__ __forceinline__ unsigned cvt_pk_bf16(float lo, float hi) { f32x2_c v = {lo, hi}; bf16x2_c r = __builtin_convertvector(v, bf16x2_c); return __builtin_bit_cast(unsigned, r); }
; __device__ __forceinline__ float siluf(float x) { return x * sigm(x); }
; __device__ __forceinline__ u32x4 pack8(const f32x4 a, const f32x4 b) { u32x4 w; w.x = cvt_pk_bf16(a[0], a[1]); w.y = cvt_pk_bf16(a[2], a[3]); w.z = cvt_pk_bf16(b[0], b[1]); w.w = cvt_pk_bf16(b[2], b[3]); return w; }
;     __device__ __forceinline__ void operator()(Acc& acc, const Unit& u, int wr, int wc, int fr, int fq) const {
;         bf16_t* base = H + u.ooff + (size_t)(wr * 64 + fr) * DFF + wc * 32 + 8 * fq;
; #pragma unroll
;         for (int ai = 0; ai < 2; ++ai)
; #pragma unroll
;             for (int m = 0; m < 4; ++m) {
;                 f32x4 h0, h1;
; #pragma unroll
;                 for (int j = 0; j < 4; ++j) { h0[j] = siluf(acc[ai][0][m][0][j]) * acc[ai][1][m][0][j]; h1[j] = siluf(acc[ai][0][m][1][j]) * acc[ai][1][m][1][j]; }
;                 *(u32x4*)(base + (size_t)(ai * 128 + m * 16) * DFF) = pack8(h0, h1);
;             }
.LBB0_122:
	v_lshl_add_u64 v[146:147], s[30:31], 1, v[136:137]
	s_mov_b32 s6, 0x2c000
	s_mov_b64 s[30:31], -1
	s_mov_b32 s6, 0x58000
	s_mov_b32 s6, 0x84000
	s_mov_b32 s6, 0x160000
	s_mov_b32 s6, 0x18c000
	s_mov_b32 s6, 0x1b8000
	s_andn2_b64 vcc, exec, s[2:3]
	s_mov_b32 s98, 0xbfb8aa3b
	s_mov_b64 s[100:101], 0x2c000
	v_pk_mul_f32 v[152:153], v[124:125], s[98:99] op_sel_hi:[1,0]
	v_pk_mul_f32 v[154:155], v[126:127], s[98:99] op_sel_hi:[1,0]
	v_pk_mul_f32 v[156:157], v[116:117], s[98:99] op_sel_hi:[1,0]
	v_pk_mul_f32 v[158:159], v[118:119], s[98:99] op_sel_hi:[1,0]
	v_pk_mul_f32 v[160:161], v[108:109], s[98:99] op_sel_hi:[1,0]
	v_pk_mul_f32 v[162:163], v[110:111], s[98:99] op_sel_hi:[1,0]
	v_pk_mul_f32 v[164:165], v[100:101], s[98:99] op_sel_hi:[1,0]
	v_pk_mul_f32 v[166:167], v[102:103], s[98:99] op_sel_hi:[1,0]
	v_exp_f32_e32 v152, v152
	v_exp_f32_e32 v153, v153
	v_exp_f32_e32 v154, v154
	v_exp_f32_e32 v155, v155
	v_exp_f32_e32 v156, v156
	v_exp_f32_e32 v157, v157
	v_exp_f32_e32 v158, v158
	v_exp_f32_e32 v159, v159
	v_exp_f32_e32 v160, v160
	v_exp_f32_e32 v161, v161
	v_exp_f32_e32 v162, v162
	v_exp_f32_e32 v163, v163
	v_exp_f32_e32 v164, v164
	v_exp_f32_e32 v165, v165
	v_exp_f32_e32 v166, v166
	v_exp_f32_e32 v167, v167
	v_pk_add_f32 v[152:153], v[152:153], 1.0 op_sel_hi:[1,0]
	v_pk_add_f32 v[154:155], v[154:155], 1.0 op_sel_hi:[1,0]
	v_pk_add_f32 v[156:157], v[156:157], 1.0 op_sel_hi:[1,0]
	v_pk_add_f32 v[158:159], v[158:159], 1.0 op_sel_hi:[1,0]
	v_pk_add_f32 v[160:161], v[160:161], 1.0 op_sel_hi:[1,0]
	v_pk_add_f32 v[162:163], v[162:163], 1.0 op_sel_hi:[1,0]
	v_pk_add_f32 v[164:165], v[164:165], 1.0 op_sel_hi:[1,0]
	v_pk_add_f32 v[166:167], v[166:167], 1.0 op_sel_hi:[1,0]
	v_rcp_f32_e32 v152, v152
	v_rcp_f32_e32 v153, v153
	v_rcp_f32_e32 v154, v154
	v_rcp_f32_e32 v155, v155
	v_rcp_f32_e32 v156, v156
	v_rcp_f32_e32 v157, v157
	v_rcp_f32_e32 v158, v158
	v_rcp_f32_e32 v159, v159
	v_rcp_f32_e32 v160, v160
	v_rcp_f32_e32 v161, v161
	v_rcp_f32_e32 v162, v162
	v_rcp_f32_e32 v163, v163
	v_rcp_f32_e32 v164, v164
	v_rcp_f32_e32 v165, v165
	v_rcp_f32_e32 v166, v166
	v_rcp_f32_e32 v167, v167
	v_pk_mul_f32 v[152:153], v[124:125], v[152:153]
	v_pk_mul_f32 v[154:155], v[126:127], v[154:155]
	v_pk_mul_f32 v[156:157], v[116:117], v[156:157]
	v_pk_mul_f32 v[158:159], v[118:119], v[158:159]
	v_pk_mul_f32 v[160:161], v[108:109], v[160:161]
	v_pk_mul_f32 v[162:163], v[110:111], v[162:163]
	v_pk_mul_f32 v[164:165], v[100:101], v[164:165]
	v_pk_mul_f32 v[166:167], v[102:103], v[166:167]
	v_pk_mul_f32 v[152:153], v[152:153], v[120:121]
	v_pk_mul_f32 v[154:155], v[154:155], v[122:123]
	v_pk_mul_f32 v[156:157], v[156:157], v[112:113]
	v_pk_mul_f32 v[158:159], v[158:159], v[114:115]
	v_pk_mul_f32 v[160:161], v[160:161], v[104:105]
	v_pk_mul_f32 v[162:163], v[162:163], v[106:107]
	v_pk_mul_f32 v[164:165], v[164:165], v[96:97]
	v_pk_mul_f32 v[166:167], v[166:167], v[98:99]
	v_cvt_pk_bf16_f32 v152, v152, v153
	v_cvt_pk_bf16_f32 v153, v154, v155
	v_cvt_pk_bf16_f32 v154, v156, v157
	v_cvt_pk_bf16_f32 v155, v158, v159
	v_cvt_pk_bf16_f32 v160, v160, v161
	v_cvt_pk_bf16_f32 v161, v162, v163
	v_cvt_pk_bf16_f32 v162, v164, v165
	v_cvt_pk_bf16_f32 v163, v166, v167
	global_store_dwordx4 v[146:147], v[152:155], off
	v_lshl_add_u64 v[146:147], v[146:147], 0, s[100:101]
	global_store_dwordx4 v[146:147], v[160:163], off
	v_lshl_add_u64 v[146:147], v[146:147], 0, s[100:101]
	v_pk_mul_f32 v[152:153], v[92:93], s[98:99] op_sel_hi:[1,0]
	v_pk_mul_f32 v[154:155], v[94:95], s[98:99] op_sel_hi:[1,0]
	v_pk_mul_f32 v[156:157], v[84:85], s[98:99] op_sel_hi:[1,0]
	v_pk_mul_f32 v[158:159], v[86:87], s[98:99] op_sel_hi:[1,0]
	v_pk_mul_f32 v[160:161], v[76:77], s[98:99] op_sel_hi:[1,0]
	v_pk_mul_f32 v[162:163], v[78:79], s[98:99] op_sel_hi:[1,0]
	v_pk_mul_f32 v[164:165], v[68:69], s[98:99] op_sel_hi:[1,0]
	v_pk_mul_f32 v[166:167], v[70:71], s[98:99] op_sel_hi:[1,0]
	v_exp_f32_e32 v152, v152
	v_exp_f32_e32 v153, v153
	v_exp_f32_e32 v154, v154
	v_exp_f32_e32 v155, v155
	v_exp_f32_e32 v156, v156
	v_exp_f32_e32 v157, v157
	v_exp_f32_e32 v158, v158
	v_exp_f32_e32 v159, v159
	v_exp_f32_e32 v160, v160
	v_exp_f32_e32 v161, v161
	v_exp_f32_e32 v162, v162
	v_exp_f32_e32 v163, v163
	v_exp_f32_e32 v164, v164
	v_exp_f32_e32 v165, v165
	v_exp_f32_e32 v166, v166
	v_exp_f32_e32 v167, v167
	v_pk_add_f32 v[152:153], v[152:153], 1.0 op_sel_hi:[1,0]
	v_pk_add_f32 v[154:155], v[154:155], 1.0 op_sel_hi:[1,0]
	v_pk_add_f32 v[156:157], v[156:157], 1.0 op_sel_hi:[1,0]
	v_pk_add_f32 v[158:159], v[158:159], 1.0 op_sel_hi:[1,0]
	v_pk_add_f32 v[160:161], v[160:161], 1.0 op_sel_hi:[1,0]
	v_pk_add_f32 v[162:163], v[162:163], 1.0 op_sel_hi:[1,0]
	v_pk_add_f32 v[164:165], v[164:165], 1.0 op_sel_hi:[1,0]
	v_pk_add_f32 v[166:167], v[166:167], 1.0 op_sel_hi:[1,0]
	v_rcp_f32_e32 v152, v152
	v_rcp_f32_e32 v153, v153
	v_rcp_f32_e32 v154, v154
	v_rcp_f32_e32 v155, v155
	v_rcp_f32_e32 v156, v156
	v_rcp_f32_e32 v157, v157
	v_rcp_f32_e32 v158, v158
	v_rcp_f32_e32 v159, v159
	v_rcp_f32_e32 v160, v160
	v_rcp_f32_e32 v161, v161
	v_rcp_f32_e32 v162, v162
	v_rcp_f32_e32 v163, v163
	v_rcp_f32_e32 v164, v164
	v_rcp_f32_e32 v165, v165
	v_rcp_f32_e32 v166, v166
	v_rcp_f32_e32 v167, v167
	v_pk_mul_f32 v[152:153], v[92:93], v[152:153]
	v_pk_mul_f32 v[154:155], v[94:95], v[154:155]
	v_pk_mul_f32 v[156:157], v[84:85], v[156:157]
	v_pk_mul_f32 v[158:159], v[86:87], v[158:159]
	v_pk_mul_f32 v[160:161], v[76:77], v[160:161]
	v_pk_mul_f32 v[162:163], v[78:79], v[162:163]
	v_pk_mul_f32 v[164:165], v[68:69], v[164:165]
	v_pk_mul_f32 v[166:167], v[70:71], v[166:167]
	v_pk_mul_f32 v[152:153], v[152:153], v[88:89]
	v_pk_mul_f32 v[154:155], v[154:155], v[90:91]
; __device__ __forceinline__ float siluf(float x) { return x * sigm(x); }
; __device__ __forceinline__ u32x4 pack8(const f32x4 a, const f32x4 b) { u32x4 w; w.x = cvt_pk_bf16(a[0], a[1]); w.y = cvt_pk_bf16(a[2], a[3]); w.z = cvt_pk_bf16(b[0], b[1]); w.w = cvt_pk_bf16(b[2], b[3]); return w; }
;     __device__ __forceinline__ void operator()(Acc& acc, const Unit& u, int wr, int wc, int fr, int fq) const {
;     ...
;         for (int ai = 0; ai < 2; ++ai)
; #pragma unroll
;             for (int m = 0; m < 4; ++m) {
;                 f32x4 h0, h1;
; #pragma unroll
;                 for (int j = 0; j < 4; ++j) { h0[j] = siluf(acc[ai][0][m][0][j]) * acc[ai][1][m][0][j]; h1[j] = siluf(acc[ai][0][m][1][j]) * acc[ai][1][m][1][j]; }
;                 *(u32x4*)(base + (size_t)(ai * 128 + m * 16) * DFF) = pack8(h0, h1);
;             }
	v_pk_mul_f32 v[156:157], v[156:157], v[80:81]
	v_pk_mul_f32 v[158:159], v[158:159], v[82:83]
	v_pk_mul_f32 v[160:161], v[160:161], v[72:73]
	v_pk_mul_f32 v[162:163], v[162:163], v[74:75]
	v_pk_mul_f32 v[164:165], v[164:165], v[64:65]
	v_pk_mul_f32 v[166:167], v[166:167], v[66:67]
	v_cvt_pk_bf16_f32 v152, v152, v153
	v_cvt_pk_bf16_f32 v153, v154, v155
	v_cvt_pk_bf16_f32 v154, v156, v157
	v_cvt_pk_bf16_f32 v155, v158, v159
	v_cvt_pk_bf16_f32 v160, v160, v161
	v_cvt_pk_bf16_f32 v161, v162, v163
	v_cvt_pk_bf16_f32 v162, v164, v165
	v_cvt_pk_bf16_f32 v163, v166, v167
	global_store_dwordx4 v[146:147], v[152:155], off
	v_lshl_add_u64 v[146:147], v[146:147], 0, s[100:101]
	global_store_dwordx4 v[146:147], v[160:163], off
	s_mov_b64 s[100:101], 0xdc000
	v_lshl_add_u64 v[146:147], v[146:147], 0, s[100:101]
	s_mov_b64 s[100:101], 0x2c000
	v_pk_mul_f32 v[152:153], v[60:61], s[98:99] op_sel_hi:[1,0]
	v_pk_mul_f32 v[154:155], v[62:63], s[98:99] op_sel_hi:[1,0]
	v_pk_mul_f32 v[156:157], v[52:53], s[98:99] op_sel_hi:[1,0]
	v_pk_mul_f32 v[158:159], v[54:55], s[98:99] op_sel_hi:[1,0]
	v_pk_mul_f32 v[160:161], v[44:45], s[98:99] op_sel_hi:[1,0]
	v_pk_mul_f32 v[162:163], v[46:47], s[98:99] op_sel_hi:[1,0]
	v_pk_mul_f32 v[164:165], v[36:37], s[98:99] op_sel_hi:[1,0]
	v_pk_mul_f32 v[166:167], v[38:39], s[98:99] op_sel_hi:[1,0]
	v_exp_f32_e32 v152, v152
	v_exp_f32_e32 v153, v153
	v_exp_f32_e32 v154, v154
	v_exp_f32_e32 v155, v155
	v_exp_f32_e32 v156, v156
	v_exp_f32_e32 v157, v157
	v_exp_f32_e32 v158, v158
	v_exp_f32_e32 v159, v159
	v_exp_f32_e32 v160, v160
	v_exp_f32_e32 v161, v161
	v_exp_f32_e32 v162, v162
	v_exp_f32_e32 v163, v163
	v_exp_f32_e32 v164, v164
	v_exp_f32_e32 v165, v165
	v_exp_f32_e32 v166, v166
	v_exp_f32_e32 v167, v167
	v_pk_add_f32 v[152:153], v[152:153], 1.0 op_sel_hi:[1,0]
	v_pk_add_f32 v[154:155], v[154:155], 1.0 op_sel_hi:[1,0]
	v_pk_add_f32 v[156:157], v[156:157], 1.0 op_sel_hi:[1,0]
	v_pk_add_f32 v[158:159], v[158:159], 1.0 op_sel_hi:[1,0]
	v_pk_add_f32 v[160:161], v[160:161], 1.0 op_sel_hi:[1,0]
	v_pk_add_f32 v[162:163], v[162:163], 1.0 op_sel_hi:[1,0]
	v_pk_add_f32 v[164:165], v[164:165], 1.0 op_sel_hi:[1,0]
	v_pk_add_f32 v[166:167], v[166:167], 1.0 op_sel_hi:[1,0]
	v_rcp_f32_e32 v152, v152
	v_rcp_f32_e32 v153, v153
	v_rcp_f32_e32 v154, v154
	v_rcp_f32_e32 v155, v155
	v_rcp_f32_e32 v156, v156
	v_rcp_f32_e32 v157, v157
	v_rcp_f32_e32 v158, v158
	v_rcp_f32_e32 v159, v159
	v_rcp_f32_e32 v160, v160
	v_rcp_f32_e32 v161, v161
	v_rcp_f32_e32 v162, v162
	v_rcp_f32_e32 v163, v163
	v_rcp_f32_e32 v164, v164
	v_rcp_f32_e32 v165, v165
	v_rcp_f32_e32 v166, v166
	v_rcp_f32_e32 v167, v167
	v_pk_mul_f32 v[152:153], v[60:61], v[152:153]
	v_pk_mul_f32 v[154:155], v[62:63], v[154:155]
	v_pk_mul_f32 v[156:157], v[52:53], v[156:157]
	v_pk_mul_f32 v[158:159], v[54:55], v[158:159]
	v_pk_mul_f32 v[160:161], v[44:45], v[160:161]
	v_pk_mul_f32 v[162:163], v[46:47], v[162:163]
	v_pk_mul_f32 v[164:165], v[36:37], v[164:165]
	v_pk_mul_f32 v[166:167], v[38:39], v[166:167]
	v_pk_mul_f32 v[152:153], v[152:153], v[56:57]
	v_pk_mul_f32 v[154:155], v[154:155], v[58:59]
	v_pk_mul_f32 v[156:157], v[156:157], v[48:49]
	v_pk_mul_f32 v[158:159], v[158:159], v[50:51]
	v_pk_mul_f32 v[160:161], v[160:161], v[40:41]
	v_pk_mul_f32 v[162:163], v[162:163], v[42:43]
	v_pk_mul_f32 v[164:165], v[164:165], v[32:33]
	v_pk_mul_f32 v[166:167], v[166:167], v[34:35]
	v_cvt_pk_bf16_f32 v152, v152, v153
	v_cvt_pk_bf16_f32 v153, v154, v155
	v_cvt_pk_bf16_f32 v154, v156, v157
	v_cvt_pk_bf16_f32 v155, v158, v159
	v_cvt_pk_bf16_f32 v160, v160, v161
	v_cvt_pk_bf16_f32 v161, v162, v163
	v_cvt_pk_bf16_f32 v162, v164, v165
	v_cvt_pk_bf16_f32 v163, v166, v167
	global_store_dwordx4 v[146:147], v[152:155], off
	v_lshl_add_u64 v[146:147], v[146:147], 0, s[100:101]
	global_store_dwordx4 v[146:147], v[160:163], off
	v_lshl_add_u64 v[146:147], v[146:147], 0, s[100:101]
	v_pk_mul_f32 v[152:153], v[28:29], s[98:99] op_sel_hi:[1,0]
	v_pk_mul_f32 v[154:155], v[30:31], s[98:99] op_sel_hi:[1,0]
	v_pk_mul_f32 v[156:157], v[20:21], s[98:99] op_sel_hi:[1,0]
	v_pk_mul_f32 v[158:159], v[22:23], s[98:99] op_sel_hi:[1,0]
	v_pk_mul_f32 v[160:161], v[12:13], s[98:99] op_sel_hi:[1,0]
	v_pk_mul_f32 v[162:163], v[14:15], s[98:99] op_sel_hi:[1,0]
	v_pk_mul_f32 v[164:165], v[4:5], s[98:99] op_sel_hi:[1,0]
	v_pk_mul_f32 v[166:167], v[6:7], s[98:99] op_sel_hi:[1,0]
	v_exp_f32_e32 v152, v152
	v_exp_f32_e32 v153, v153
	v_exp_f32_e32 v154, v154
	v_exp_f32_e32 v155, v155
	v_exp_f32_e32 v156, v156
	v_exp_f32_e32 v157, v157
	v_exp_f32_e32 v158, v158
	v_exp_f32_e32 v159, v159
	v_exp_f32_e32 v160, v160
	v_exp_f32_e32 v161, v161
	v_exp_f32_e32 v162, v162
	v_exp_f32_e32 v163, v163
	v_exp_f32_e32 v164, v164
	v_exp_f32_e32 v165, v165
	v_exp_f32_e32 v166, v166
	v_exp_f32_e32 v167, v167
	v_pk_add_f32 v[152:153], v[152:153], 1.0 op_sel_hi:[1,0]
	v_pk_add_f32 v[154:155], v[154:155], 1.0 op_sel_hi:[1,0]
	v_pk_add_f32 v[156:157], v[156:157], 1.0 op_sel_hi:[1,0]
	v_pk_add_f32 v[158:159], v[158:159], 1.0 op_sel_hi:[1,0]
	v_pk_add_f32 v[160:161], v[160:161], 1.0 op_sel_hi:[1,0]
	v_pk_add_f32 v[162:163], v[162:163], 1.0 op_sel_hi:[1,0]
	v_pk_add_f32 v[164:165], v[164:165], 1.0 op_sel_hi:[1,0]
	v_pk_add_f32 v[166:167], v[166:167], 1.0 op_sel_hi:[1,0]
	v_rcp_f32_e32 v152, v152
	v_rcp_f32_e32 v153, v153
	v_rcp_f32_e32 v154, v154
	v_rcp_f32_e32 v155, v155
	v_rcp_f32_e32 v156, v156
	v_rcp_f32_e32 v157, v157
	v_rcp_f32_e32 v158, v158
	v_rcp_f32_e32 v159, v159
	v_rcp_f32_e32 v160, v160
	v_rcp_f32_e32 v161, v161
	v_rcp_f32_e32 v162, v162
	v_rcp_f32_e32 v163, v163
	v_rcp_f32_e32 v164, v164
	v_rcp_f32_e32 v165, v165
	v_rcp_f32_e32 v166, v166
	v_rcp_f32_e32 v167, v167
	v_pk_mul_f32 v[152:153], v[28:29], v[152:153]
	v_pk_mul_f32 v[154:155], v[30:31], v[154:155]
	v_pk_mul_f32 v[156:157], v[20:21], v[156:157]
	v_pk_mul_f32 v[158:159], v[22:23], v[158:159]
	v_pk_mul_f32 v[160:161], v[12:13], v[160:161]
	v_pk_mul_f32 v[162:163], v[14:15], v[162:163]
	v_pk_mul_f32 v[164:165], v[4:5], v[164:165]
	v_pk_mul_f32 v[166:167], v[6:7], v[166:167]
	v_pk_mul_f32 v[152:153], v[152:153], v[24:25]
	v_pk_mul_f32 v[154:155], v[154:155], v[26:27]
	v_pk_mul_f32 v[156:157], v[156:157], v[16:17]
	v_pk_mul_f32 v[158:159], v[158:159], v[18:19]
	v_pk_mul_f32 v[160:161], v[160:161], v[8:9]
	v_pk_mul_f32 v[162:163], v[162:163], v[10:11]
	v_pk_mul_f32 v[164:165], v[164:165], v[0:1]
	v_pk_mul_f32 v[166:167], v[166:167], v[2:3]
	v_cvt_pk_bf16_f32 v152, v152, v153
	v_cvt_pk_bf16_f32 v153, v154, v155
	v_cvt_pk_bf16_f32 v154, v156, v157
	v_cvt_pk_bf16_f32 v155, v158, v159
	v_cvt_pk_bf16_f32 v160, v160, v161
	v_cvt_pk_bf16_f32 v161, v162, v163
	v_cvt_pk_bf16_f32 v162, v164, v165
	v_cvt_pk_bf16_f32 v163, v166, v167
	global_store_dwordx4 v[146:147], v[152:155], off
	v_lshl_add_u64 v[146:147], v[146:147], 0, s[100:101]
	global_store_dwordx4 v[146:147], v[160:163], off
	s_cbranch_vccnz .LBB0_115
	s_andn2_b64 vcc, exec, s[14:15]
	s_cbranch_vccnz .LBB0_114
	s_barrier
	s_branch .LBB0_114

; __device__ __forceinline__ unsigned cvt_pk_bf16(float lo, float hi) { f32x2_c v = {lo, hi}; bf16x2_c r = __builtin_convertvector(v, bf16x2_c); return __builtin_bit_cast(unsigned, r); }
; __device__ __forceinline__ float siluf(float x) { return x * sigm(x); }
; __device__ __forceinline__ u32x4 pack8(const f32x4 a, const f32x4 b) { u32x4 w; w.x = cvt_pk_bf16(a[0], a[1]); w.y = cvt_pk_bf16(a[2], a[3]); w.z = cvt_pk_bf16(b[0], b[1]); w.w = cvt_pk_bf16(b[2], b[3]); return w; }
;     __device__ __forceinline__ void operator()(Acc& acc, const Unit& u, int wr, int wc, int fr, int fq) const {
;         bf16_t* base = H + u.ooff + (size_t)(wr * 64 + fr) * DFF + wc * 32 + 8 * fq;
; #pragma unroll
;         for (int ai = 0; ai < 2; ++ai)
; #pragma unroll
;             for (int m = 0; m < 4; ++m) {
;                 f32x4 h0, h1;
; #pragma unroll
;                 for (int j = 0; j < 4; ++j) { h0[j] = siluf(acc[ai][0][m][0][j]) * acc[ai][1][m][0][j]; h1[j] = siluf(acc[ai][0][m][1][j]) * acc[ai][1][m][1][j]; }
;                 *(u32x4*)(base + (size_t)(ai * 128 + m * 16) * DFF) = pack8(h0, h1);
;             }
.LBB0_1372:
	v_lshl_add_u64 v[146:147], s[22:23], 1, v[136:137]
	s_andn2_b64 vcc, exec, s[2:3]
	s_mov_b64 s[2:3], -1
	s_mov_b32 s98, 0xbfb8aa3b
	s_mov_b64 s[100:101], 0x2c000
	v_pk_mul_f32 v[152:153], v[124:125], s[98:99] op_sel_hi:[1,0]
	v_pk_mul_f32 v[154:155], v[126:127], s[98:99] op_sel_hi:[1,0]
	v_pk_mul_f32 v[156:157], v[120:121], s[98:99] op_sel_hi:[1,0]
	v_pk_mul_f32 v[158:159], v[122:123], s[98:99] op_sel_hi:[1,0]
	v_pk_mul_f32 v[160:161], v[108:109], s[98:99] op_sel_hi:[1,0]
	v_pk_mul_f32 v[162:163], v[110:111], s[98:99] op_sel_hi:[1,0]
	v_pk_mul_f32 v[168:169], v[104:105], s[98:99] op_sel_hi:[1,0]
	v_pk_mul_f32 v[170:171], v[106:107], s[98:99] op_sel_hi:[1,0]
	v_exp_f32_e32 v152, v152
	v_exp_f32_e32 v153, v153
	v_exp_f32_e32 v154, v154
	v_exp_f32_e32 v155, v155
	v_exp_f32_e32 v156, v156
	v_exp_f32_e32 v157, v157
	v_exp_f32_e32 v158, v158
	v_exp_f32_e32 v159, v159
	v_exp_f32_e32 v160, v160
	v_exp_f32_e32 v161, v161
	v_exp_f32_e32 v162, v162
	v_exp_f32_e32 v163, v163
	v_exp_f32_e32 v168, v168
	v_exp_f32_e32 v169, v169
	v_exp_f32_e32 v170, v170
	v_exp_f32_e32 v171, v171
	v_pk_add_f32 v[152:153], v[152:153], 1.0 op_sel_hi:[1,0]
	v_pk_add_f32 v[154:155], v[154:155], 1.0 op_sel_hi:[1,0]
	v_pk_add_f32 v[156:157], v[156:157], 1.0 op_sel_hi:[1,0]
	v_pk_add_f32 v[158:159], v[158:159], 1.0 op_sel_hi:[1,0]
	v_pk_add_f32 v[160:161], v[160:161], 1.0 op_sel_hi:[1,0]
	v_pk_add_f32 v[162:163], v[162:163], 1.0 op_sel_hi:[1,0]
	v_pk_add_f32 v[168:169], v[168:169], 1.0 op_sel_hi:[1,0]
	v_pk_add_f32 v[170:171], v[170:171], 1.0 op_sel_hi:[1,0]
	v_rcp_f32_e32 v152, v152
	v_rcp_f32_e32 v153, v153
	v_rcp_f32_e32 v154, v154
	v_rcp_f32_e32 v155, v155
	v_rcp_f32_e32 v156, v156
	v_rcp_f32_e32 v157, v157
	v_rcp_f32_e32 v158, v158
	v_rcp_f32_e32 v159, v159
	v_rcp_f32_e32 v160, v160
	v_rcp_f32_e32 v161, v161
	v_rcp_f32_e32 v162, v162
	v_rcp_f32_e32 v163, v163
	v_rcp_f32_e32 v168, v168
	v_rcp_f32_e32 v169, v169
	v_rcp_f32_e32 v170, v170
	v_rcp_f32_e32 v171, v171
	v_pk_mul_f32 v[152:153], v[124:125], v[152:153]
	v_pk_mul_f32 v[154:155], v[126:127], v[154:155]
	v_pk_mul_f32 v[156:157], v[120:121], v[156:157]
	v_pk_mul_f32 v[158:159], v[122:123], v[158:159]
	v_pk_mul_f32 v[160:161], v[108:109], v[160:161]
	v_pk_mul_f32 v[162:163], v[110:111], v[162:163]
	v_pk_mul_f32 v[168:169], v[104:105], v[168:169]
	v_pk_mul_f32 v[170:171], v[106:107], v[170:171]
	v_pk_mul_f32 v[152:153], v[152:153], v[116:117]
	v_pk_mul_f32 v[154:155], v[154:155], v[118:119]
	v_pk_mul_f32 v[156:157], v[156:157], v[112:113]
	v_pk_mul_f32 v[158:159], v[158:159], v[114:115]
	v_pk_mul_f32 v[160:161], v[160:161], v[100:101]
	v_pk_mul_f32 v[162:163], v[162:163], v[102:103]
	v_pk_mul_f32 v[168:169], v[168:169], v[96:97]
	v_pk_mul_f32 v[170:171], v[170:171], v[98:99]
	v_cvt_pk_bf16_f32 v152, v152, v153
	v_cvt_pk_bf16_f32 v153, v154, v155
	v_cvt_pk_bf16_f32 v154, v156, v157
	v_cvt_pk_bf16_f32 v155, v158, v159
	v_cvt_pk_bf16_f32 v160, v160, v161
	v_cvt_pk_bf16_f32 v161, v162, v163
	v_cvt_pk_bf16_f32 v162, v168, v169
	v_cvt_pk_bf16_f32 v163, v170, v171
	global_store_dwordx4 v[146:147], v[152:155], off
	v_lshl_add_u64 v[146:147], v[146:147], 0, s[100:101]
	global_store_dwordx4 v[146:147], v[160:163], off
	v_lshl_add_u64 v[146:147], v[146:147], 0, s[100:101]
	v_pk_mul_f32 v[152:153], v[92:93], s[98:99] op_sel_hi:[1,0]
	v_pk_mul_f32 v[154:155], v[94:95], s[98:99] op_sel_hi:[1,0]
	v_pk_mul_f32 v[156:157], v[88:89], s[98:99] op_sel_hi:[1,0]
	v_pk_mul_f32 v[158:159], v[90:91], s[98:99] op_sel_hi:[1,0]
	v_pk_mul_f32 v[160:161], v[76:77], s[98:99] op_sel_hi:[1,0]
	v_pk_mul_f32 v[162:163], v[78:79], s[98:99] op_sel_hi:[1,0]
	v_pk_mul_f32 v[168:169], v[72:73], s[98:99] op_sel_hi:[1,0]
	v_pk_mul_f32 v[170:171], v[74:75], s[98:99] op_sel_hi:[1,0]
	v_exp_f32_e32 v152, v152
	v_exp_f32_e32 v153, v153
	v_exp_f32_e32 v154, v154
	v_exp_f32_e32 v155, v155
	v_exp_f32_e32 v156, v156
	v_exp_f32_e32 v157, v157
	v_exp_f32_e32 v158, v158
	v_exp_f32_e32 v159, v159
	v_exp_f32_e32 v160, v160
	v_exp_f32_e32 v161, v161
	v_exp_f32_e32 v162, v162
	v_exp_f32_e32 v163, v163
	v_exp_f32_e32 v168, v168
	v_exp_f32_e32 v169, v169
	v_exp_f32_e32 v170, v170
	v_exp_f32_e32 v171, v171
	v_pk_add_f32 v[152:153], v[152:153], 1.0 op_sel_hi:[1,0]
	v_pk_add_f32 v[154:155], v[154:155], 1.0 op_sel_hi:[1,0]
	v_pk_add_f32 v[156:157], v[156:157], 1.0 op_sel_hi:[1,0]
	v_pk_add_f32 v[158:159], v[158:159], 1.0 op_sel_hi:[1,0]
	v_pk_add_f32 v[160:161], v[160:161], 1.0 op_sel_hi:[1,0]
	v_pk_add_f32 v[162:163], v[162:163], 1.0 op_sel_hi:[1,0]
	v_pk_add_f32 v[168:169], v[168:169], 1.0 op_sel_hi:[1,0]
	v_pk_add_f32 v[170:171], v[170:171], 1.0 op_sel_hi:[1,0]
	v_rcp_f32_e32 v152, v152
	v_rcp_f32_e32 v153, v153
	v_rcp_f32_e32 v154, v154
	v_rcp_f32_e32 v155, v155
	v_rcp_f32_e32 v156, v156
	v_rcp_f32_e32 v157, v157
	v_rcp_f32_e32 v158, v158
	v_rcp_f32_e32 v159, v159
	v_rcp_f32_e32 v160, v160
	v_rcp_f32_e32 v161, v161
	v_rcp_f32_e32 v162, v162
	v_rcp_f32_e32 v163, v163
	v_rcp_f32_e32 v168, v168
	v_rcp_f32_e32 v169, v169
	v_rcp_f32_e32 v170, v170
	v_rcp_f32_e32 v171, v171
	v_pk_mul_f32 v[152:153], v[92:93], v[152:153]
	v_pk_mul_f32 v[154:155], v[94:95], v[154:155]
	v_pk_mul_f32 v[156:157], v[88:89], v[156:157]
	v_pk_mul_f32 v[158:159], v[90:91], v[158:159]
	v_pk_mul_f32 v[160:161], v[76:77], v[160:161]
	v_pk_mul_f32 v[162:163], v[78:79], v[162:163]
	v_pk_mul_f32 v[168:169], v[72:73], v[168:169]
	v_pk_mul_f32 v[170:171], v[74:75], v[170:171]
	v_pk_mul_f32 v[152:153], v[152:153], v[84:85]
	v_pk_mul_f32 v[154:155], v[154:155], v[86:87]
	v_pk_mul_f32 v[156:157], v[156:157], v[80:81]
	v_pk_mul_f32 v[158:159], v[158:159], v[82:83]
	v_pk_mul_f32 v[160:161], v[160:161], v[68:69]
; __device__ __forceinline__ float siluf(float x) { return x * sigm(x); }
; __device__ __forceinline__ u32x4 pack8(const f32x4 a, const f32x4 b) { u32x4 w; w.x = cvt_pk_bf16(a[0], a[1]); w.y = cvt_pk_bf16(a[2], a[3]); w.z = cvt_pk_bf16(b[0], b[1]); w.w = cvt_pk_bf16(b[2], b[3]); return w; }
;     __device__ __forceinline__ void operator()(Acc& acc, const Unit& u, int wr, int wc, int fr, int fq) const {
;     ...
;         for (int ai = 0; ai < 2; ++ai)
; #pragma unroll
;             for (int m = 0; m < 4; ++m) {
;                 f32x4 h0, h1;
; #pragma unroll
;                 for (int j = 0; j < 4; ++j) { h0[j] = siluf(acc[ai][0][m][0][j]) * acc[ai][1][m][0][j]; h1[j] = siluf(acc[ai][0][m][1][j]) * acc[ai][1][m][1][j]; }
;                 *(u32x4*)(base + (size_t)(ai * 128 + m * 16) * DFF) = pack8(h0, h1);
;             }
	v_pk_mul_f32 v[162:163], v[162:163], v[70:71]
	v_pk_mul_f32 v[168:169], v[168:169], v[64:65]
	v_pk_mul_f32 v[170:171], v[170:171], v[66:67]
	v_cvt_pk_bf16_f32 v152, v152, v153
	v_cvt_pk_bf16_f32 v153, v154, v155
	v_cvt_pk_bf16_f32 v154, v156, v157
	v_cvt_pk_bf16_f32 v155, v158, v159
	v_cvt_pk_bf16_f32 v160, v160, v161
	v_cvt_pk_bf16_f32 v161, v162, v163
	v_cvt_pk_bf16_f32 v162, v168, v169
	v_cvt_pk_bf16_f32 v163, v170, v171
	global_store_dwordx4 v[146:147], v[152:155], off
	v_lshl_add_u64 v[146:147], v[146:147], 0, s[100:101]
	global_store_dwordx4 v[146:147], v[160:163], off
	s_mov_b64 s[100:101], 0xdc000
	v_lshl_add_u64 v[146:147], v[146:147], 0, s[100:101]
	s_mov_b64 s[100:101], 0x2c000
	v_pk_mul_f32 v[152:153], v[60:61], s[98:99] op_sel_hi:[1,0]
	v_pk_mul_f32 v[154:155], v[62:63], s[98:99] op_sel_hi:[1,0]
	v_pk_mul_f32 v[156:157], v[56:57], s[98:99] op_sel_hi:[1,0]
	v_pk_mul_f32 v[158:159], v[58:59], s[98:99] op_sel_hi:[1,0]
	v_pk_mul_f32 v[160:161], v[44:45], s[98:99] op_sel_hi:[1,0]
	v_pk_mul_f32 v[162:163], v[46:47], s[98:99] op_sel_hi:[1,0]
	v_pk_mul_f32 v[168:169], v[40:41], s[98:99] op_sel_hi:[1,0]
	v_pk_mul_f32 v[170:171], v[42:43], s[98:99] op_sel_hi:[1,0]
	v_exp_f32_e32 v152, v152
	v_exp_f32_e32 v153, v153
	v_exp_f32_e32 v154, v154
	v_exp_f32_e32 v155, v155
	v_exp_f32_e32 v156, v156
	v_exp_f32_e32 v157, v157
	v_exp_f32_e32 v158, v158
	v_exp_f32_e32 v159, v159
	v_exp_f32_e32 v160, v160
	v_exp_f32_e32 v161, v161
	v_exp_f32_e32 v162, v162
	v_exp_f32_e32 v163, v163
	v_exp_f32_e32 v168, v168
	v_exp_f32_e32 v169, v169
	v_exp_f32_e32 v170, v170
	v_exp_f32_e32 v171, v171
	v_pk_add_f32 v[152:153], v[152:153], 1.0 op_sel_hi:[1,0]
	v_pk_add_f32 v[154:155], v[154:155], 1.0 op_sel_hi:[1,0]
	v_pk_add_f32 v[156:157], v[156:157], 1.0 op_sel_hi:[1,0]
	v_pk_add_f32 v[158:159], v[158:159], 1.0 op_sel_hi:[1,0]
	v_pk_add_f32 v[160:161], v[160:161], 1.0 op_sel_hi:[1,0]
	v_pk_add_f32 v[162:163], v[162:163], 1.0 op_sel_hi:[1,0]
	v_pk_add_f32 v[168:169], v[168:169], 1.0 op_sel_hi:[1,0]
	v_pk_add_f32 v[170:171], v[170:171], 1.0 op_sel_hi:[1,0]
	v_rcp_f32_e32 v152, v152
	v_rcp_f32_e32 v153, v153
	v_rcp_f32_e32 v154, v154
	v_rcp_f32_e32 v155, v155
	v_rcp_f32_e32 v156, v156
	v_rcp_f32_e32 v157, v157
	v_rcp_f32_e32 v158, v158
	v_rcp_f32_e32 v159, v159
	v_rcp_f32_e32 v160, v160
	v_rcp_f32_e32 v161, v161
	v_rcp_f32_e32 v162, v162
	v_rcp_f32_e32 v163, v163
	v_rcp_f32_e32 v168, v168
	v_rcp_f32_e32 v169, v169
	v_rcp_f32_e32 v170, v170
	v_rcp_f32_e32 v171, v171
	v_pk_mul_f32 v[152:153], v[60:61], v[152:153]
	v_pk_mul_f32 v[154:155], v[62:63], v[154:155]
	v_pk_mul_f32 v[156:157], v[56:57], v[156:157]
	v_pk_mul_f32 v[158:159], v[58:59], v[158:159]
	v_pk_mul_f32 v[160:161], v[44:45], v[160:161]
	v_pk_mul_f32 v[162:163], v[46:47], v[162:163]
	v_pk_mul_f32 v[168:169], v[40:41], v[168:169]
	v_pk_mul_f32 v[170:171], v[42:43], v[170:171]
	v_pk_mul_f32 v[152:153], v[152:153], v[52:53]
	v_pk_mul_f32 v[154:155], v[154:155], v[54:55]
	v_pk_mul_f32 v[156:157], v[156:157], v[48:49]
	v_pk_mul_f32 v[158:159], v[158:159], v[50:51]
	v_pk_mul_f32 v[160:161], v[160:161], v[36:37]
	v_pk_mul_f32 v[162:163], v[162:163], v[38:39]
	v_pk_mul_f32 v[168:169], v[168:169], v[32:33]
	v_pk_mul_f32 v[170:171], v[170:171], v[34:35]
	v_cvt_pk_bf16_f32 v152, v152, v153
	v_cvt_pk_bf16_f32 v153, v154, v155
	v_cvt_pk_bf16_f32 v154, v156, v157
	v_cvt_pk_bf16_f32 v155, v158, v159
	v_cvt_pk_bf16_f32 v160, v160, v161
	v_cvt_pk_bf16_f32 v161, v162, v163
	v_cvt_pk_bf16_f32 v162, v168, v169
	v_cvt_pk_bf16_f32 v163, v170, v171
	global_store_dwordx4 v[146:147], v[152:155], off
	v_lshl_add_u64 v[146:147], v[146:147], 0, s[100:101]
	global_store_dwordx4 v[146:147], v[160:163], off
	v_lshl_add_u64 v[146:147], v[146:147], 0, s[100:101]
	v_pk_mul_f32 v[152:153], v[28:29], s[98:99] op_sel_hi:[1,0]
	v_pk_mul_f32 v[154:155], v[30:31], s[98:99] op_sel_hi:[1,0]
	v_pk_mul_f32 v[156:157], v[24:25], s[98:99] op_sel_hi:[1,0]
	v_pk_mul_f32 v[158:159], v[26:27], s[98:99] op_sel_hi:[1,0]
	v_pk_mul_f32 v[160:161], v[12:13], s[98:99] op_sel_hi:[1,0]
	v_pk_mul_f32 v[162:163], v[14:15], s[98:99] op_sel_hi:[1,0]
	v_pk_mul_f32 v[168:169], v[8:9], s[98:99] op_sel_hi:[1,0]
	v_pk_mul_f32 v[170:171], v[10:11], s[98:99] op_sel_hi:[1,0]
	v_exp_f32_e32 v152, v152
	v_exp_f32_e32 v153, v153
	v_exp_f32_e32 v154, v154
	v_exp_f32_e32 v155, v155
	v_exp_f32_e32 v156, v156
	v_exp_f32_e32 v157, v157
	v_exp_f32_e32 v158, v158
	v_exp_f32_e32 v159, v159
	v_exp_f32_e32 v160, v160
	v_exp_f32_e32 v161, v161
	v_exp_f32_e32 v162, v162
	v_exp_f32_e32 v163, v163
	v_exp_f32_e32 v168, v168
	v_exp_f32_e32 v169, v169
	v_exp_f32_e32 v170, v170
	v_exp_f32_e32 v171, v171
	v_pk_add_f32 v[152:153], v[152:153], 1.0 op_sel_hi:[1,0]
	v_pk_add_f32 v[154:155], v[154:155], 1.0 op_sel_hi:[1,0]
	v_pk_add_f32 v[156:157], v[156:157], 1.0 op_sel_hi:[1,0]
	v_pk_add_f32 v[158:159], v[158:159], 1.0 op_sel_hi:[1,0]
	v_pk_add_f32 v[160:161], v[160:161], 1.0 op_sel_hi:[1,0]
	v_pk_add_f32 v[162:163], v[162:163], 1.0 op_sel_hi:[1,0]
	v_pk_add_f32 v[168:169], v[168:169], 1.0 op_sel_hi:[1,0]
	v_pk_add_f32 v[170:171], v[170:171], 1.0 op_sel_hi:[1,0]
	v_rcp_f32_e32 v152, v152
	v_rcp_f32_e32 v153, v153
	v_rcp_f32_e32 v154, v154
	v_rcp_f32_e32 v155, v155
	v_rcp_f32_e32 v156, v156
	v_rcp_f32_e32 v157, v157
	v_rcp_f32_e32 v158, v158
	v_rcp_f32_e32 v159, v159
	v_rcp_f32_e32 v160, v160
	v_rcp_f32_e32 v161, v161
	v_rcp_f32_e32 v162, v162
	v_rcp_f32_e32 v163, v163
	v_rcp_f32_e32 v168, v168
	v_rcp_f32_e32 v169, v169
	v_rcp_f32_e32 v170, v170
	v_rcp_f32_e32 v171, v171
	v_pk_mul_f32 v[152:153], v[28:29], v[152:153]
	v_pk_mul_f32 v[154:155], v[30:31], v[154:155]
	v_pk_mul_f32 v[156:157], v[24:25], v[156:157]
	v_pk_mul_f32 v[158:159], v[26:27], v[158:159]
	v_pk_mul_f32 v[160:161], v[12:13], v[160:161]
	v_pk_mul_f32 v[162:163], v[14:15], v[162:163]
	v_pk_mul_f32 v[168:169], v[8:9], v[168:169]
	v_pk_mul_f32 v[170:171], v[10:11], v[170:171]
	v_pk_mul_f32 v[152:153], v[152:153], v[20:21]
	v_pk_mul_f32 v[154:155], v[154:155], v[22:23]
	v_pk_mul_f32 v[156:157], v[156:157], v[16:17]
	v_pk_mul_f32 v[158:159], v[158:159], v[18:19]
	v_pk_mul_f32 v[160:161], v[160:161], v[4:5]
	v_pk_mul_f32 v[162:163], v[162:163], v[6:7]
	v_pk_mul_f32 v[168:169], v[168:169], v[0:1]
	v_pk_mul_f32 v[170:171], v[170:171], v[2:3]
	v_cvt_pk_bf16_f32 v152, v152, v153
	v_cvt_pk_bf16_f32 v153, v154, v155
	v_cvt_pk_bf16_f32 v154, v156, v157
	v_cvt_pk_bf16_f32 v155, v158, v159
	v_cvt_pk_bf16_f32 v160, v160, v161
	v_cvt_pk_bf16_f32 v161, v162, v163
	v_cvt_pk_bf16_f32 v162, v168, v169
	v_cvt_pk_bf16_f32 v163, v170, v171
	global_store_dwordx4 v[146:147], v[152:155], off
	v_lshl_add_u64 v[146:147], v[146:147], 0, s[100:101]
	global_store_dwordx4 v[146:147], v[160:163], off
	s_cbranch_vccnz .LBB0_1365
	s_andn2_b64 vcc, exec, s[6:7]
	s_cbranch_vccnz .LBB0_1364
	s_barrier
	s_branch .LBB0_1364
